# GLA output epilogue (norm*gain*silu gate -> bf16) rewritten: all 54 loads of a wave issued up front via saddr addressing, counted vmcnt waits instead of 96 full drains, lane-pair exchange by DPP
# speedup vs baseline: 1.0234x; 1.0212x over previous
.LBB0_4897:
	s_or_b64 exec, exec, s[22:23]
	v_lshl_or_b32 v62, v83, 2, v73
	v_or_b32_e32 v48, s0, v71
	v_add_u32_e32 v52, v82, v48
	v_or_b32_e32 v54, s66, v62
	v_mov_b64_e32 v[48:49], s[36:37]
	v_mad_i64_i32 v[48:49], s[0:1], v54, s49, v[48:49]
	v_ashrrev_i32_e32 v53, 31, v52
	v_lshl_add_u64 v[60:61], v[52:53], 1, v[48:49]
	v_add_co_u32_e32 v48, vcc, s50, v60
	s_waitcnt lgkmcnt(0)
	s_nop 0
	v_addc_co_u32_e32 v49, vcc, 0, v61, vcc
	s_barrier
	s_mov_b32 s98, 0x55555555
	s_mov_b32 s99, 0x55555555
	v_lshlrev_b32_e32 v55, 2, v52
	v_mul_lo_u32 v201, v54, s49
	global_load_dword v195, v55, s[34:35]
	global_load_dword v196, v55, s[34:35] offset:512
	global_load_dword v197, v55, s[34:35] offset:1024
	global_load_dword v198, v55, s[20:21]
	global_load_dword v199, v55, s[20:21] offset:512
	global_load_dword v200, v55, s[20:21] offset:1024
	v_lshl_add_u32 v201, v52, 1, v201
	v_add_u32_e32 v201, 0x1000, v201
	v_lshl_add_u32 v203, v62, 4, 0
	v_add_u32_e32 v203, 0x20800, v203
	ds_read_b128 v[64:67], v203
	v_lshlrev_b32_e32 v202, 12, v54
	v_lshl_add_u32 v202, v52, 1, v202
	global_load_ushort v205, v201, s[36:37] offset:2048
	global_load_ushort v206, v201, s[36:37] offset:2304
	global_load_ushort v207, v201, s[36:37] offset:2560
	v_add_u32_e32 v201, 0x2a00, v201
	global_load_ushort v208, v201, s[36:37] offset:2048
	global_load_ushort v209, v201, s[36:37] offset:2304
	global_load_ushort v210, v201, s[36:37] offset:2560
	v_add_u32_e32 v201, 0x2a00, v201
	global_load_ushort v211, v201, s[36:37] offset:2048
	global_load_ushort v212, v201, s[36:37] offset:2304
	global_load_ushort v213, v201, s[36:37] offset:2560
	v_add_u32_e32 v201, 0x2a00, v201
	global_load_ushort v214, v201, s[36:37] offset:2048
	global_load_ushort v215, v201, s[36:37] offset:2304
	global_load_ushort v216, v201, s[36:37] offset:2560
	v_add_u32_e32 v201, 0xd200, v201
	global_load_ushort v217, v201, s[36:37] offset:2048
	global_load_ushort v218, v201, s[36:37] offset:2304
	global_load_ushort v219, v201, s[36:37] offset:2560
	v_add_u32_e32 v201, 0x2a00, v201
	global_load_ushort v220, v201, s[36:37] offset:2048
	global_load_ushort v221, v201, s[36:37] offset:2304
	global_load_ushort v222, v201, s[36:37] offset:2560
	v_add_u32_e32 v201, 0x2a00, v201
	global_load_ushort v223, v201, s[36:37] offset:2048
	global_load_ushort v224, v201, s[36:37] offset:2304
	global_load_ushort v225, v201, s[36:37] offset:2560
	v_add_u32_e32 v201, 0x2a00, v201
	global_load_ushort v226, v201, s[36:37] offset:2048
	global_load_ushort v227, v201, s[36:37] offset:2304
	global_load_ushort v228, v201, s[36:37] offset:2560
	v_add_u32_e32 v201, 0xd200, v201
	global_load_ushort v229, v201, s[36:37] offset:2048
	global_load_ushort v230, v201, s[36:37] offset:2304
	global_load_ushort v231, v201, s[36:37] offset:2560
	v_add_u32_e32 v201, 0x2a00, v201
	global_load_ushort v232, v201, s[36:37] offset:2048
	global_load_ushort v233, v201, s[36:37] offset:2304
	global_load_ushort v234, v201, s[36:37] offset:2560
	v_add_u32_e32 v201, 0x2a00, v201
	global_load_ushort v235, v201, s[36:37] offset:2048
	global_load_ushort v236, v201, s[36:37] offset:2304
	global_load_ushort v237, v201, s[36:37] offset:2560
	v_add_u32_e32 v201, 0x2a00, v201
	global_load_ushort v238, v201, s[36:37] offset:2048
	global_load_ushort v239, v201, s[36:37] offset:2304
	global_load_ushort v240, v201, s[36:37] offset:2560
	v_add_u32_e32 v201, 0xd200, v201
	global_load_ushort v241, v201, s[36:37] offset:2048
	global_load_ushort v242, v201, s[36:37] offset:2304
	global_load_ushort v243, v201, s[36:37] offset:2560
	v_add_u32_e32 v201, 0x2a00, v201
	global_load_ushort v244, v201, s[36:37] offset:2048
	global_load_ushort v245, v201, s[36:37] offset:2304
	global_load_ushort v246, v201, s[36:37] offset:2560
	v_add_u32_e32 v201, 0x2a00, v201
	global_load_ushort v247, v201, s[36:37] offset:2048
	global_load_ushort v248, v201, s[36:37] offset:2304
	global_load_ushort v249, v201, s[36:37] offset:2560
	v_add_u32_e32 v201, 0x2a00, v201
	global_load_ushort v250, v201, s[36:37] offset:2048
	global_load_ushort v251, v201, s[36:37] offset:2304
	global_load_ushort v194, v201, s[36:37] offset:2560
	s_waitcnt lgkmcnt(0)
	v_add_f32_e32 v68, v64, v65
	v_add_f32_e32 v69, v66, v67
	ds_read_b128 v[64:67], v203 offset:16
	v_add_f32_e32 v68, v68, v69
	v_fmamk_f32 v68, v68, 0x3b2aaaab, v76
	v_mul_f32_e32 v69, 0x4b800000, v68
	v_cmp_gt_f32_e32 vcc, s56, v68
	s_nop 1
	v_cndmask_b32_e32 v68, v68, v69, vcc
	v_rsq_f32_e32 v68, v68
	s_nop 0
	v_mul_f32_e32 v69, 0x45800000, v68
	v_cndmask_b32_e32 v63, v68, v69, vcc
	s_waitcnt vmcnt(47)
	v_lshlrev_b32_e32 v205, 16, v205
	v_add_f32_e32 v205, v195, v205
	v_mul_f32_e32 v68, 0xbfb8aa3b, v205
	v_exp_f32_e32 v68, v68
	v_mul_f32_e32 v0, v0, v63
	v_add_f32_e32 v68, 1.0, v68
	v_div_scale_f32 v69, s[0:1], v68, v68, v205
	v_div_scale_f32 v71, vcc, v205, v68, v205
	v_rcp_f32_e32 v70, v69
	v_mul_f32_e32 v0, v198, v0
	v_fma_f32 v50, -v69, v70, 1.0
	v_fmac_f32_e32 v70, v50, v70
	v_mul_f32_e32 v50, v71, v70
	v_fma_f32 v51, -v69, v50, v71
	v_fmac_f32_e32 v50, v51, v70
	v_fma_f32 v69, -v69, v50, v71
	v_div_fmas_f32 v69, v69, v70, v50
	v_div_fixup_f32 v205, v69, v68, v205
	v_mul_f32_e32 v0, v205, v0
	s_waitcnt vmcnt(46)
	v_lshlrev_b32_e32 v206, 16, v206
	v_add_f32_e32 v206, v196, v206
	v_mul_f32_e32 v68, 0xbfb8aa3b, v206
	v_exp_f32_e32 v68, v68
	v_mul_f32_e32 v16, v16, v63
	v_add_f32_e32 v68, 1.0, v68
	v_div_scale_f32 v69, s[0:1], v68, v68, v206
	v_div_scale_f32 v71, vcc, v206, v68, v206
	v_rcp_f32_e32 v70, v69
	v_mul_f32_e32 v16, v199, v16
	v_fma_f32 v50, -v69, v70, 1.0
	v_fmac_f32_e32 v70, v50, v70
	v_mul_f32_e32 v50, v71, v70
	v_fma_f32 v51, -v69, v50, v71
	v_fmac_f32_e32 v50, v51, v70
	v_fma_f32 v69, -v69, v50, v71
	v_div_fmas_f32 v69, v69, v70, v50
	v_div_fixup_f32 v206, v69, v68, v206
	v_mul_f32_e32 v16, v206, v16
	s_waitcnt vmcnt(45)
	v_lshlrev_b32_e32 v207, 16, v207
	v_add_f32_e32 v207, v197, v207
	v_mul_f32_e32 v68, 0xbfb8aa3b, v207
	v_exp_f32_e32 v68, v68
	v_mul_f32_e32 v32, v32, v63
	v_add_f32_e32 v68, 1.0, v68
	v_div_scale_f32 v69, s[0:1], v68, v68, v207
	v_div_scale_f32 v71, vcc, v207, v68, v207
	v_rcp_f32_e32 v70, v69
	v_mul_f32_e32 v32, v200, v32
	v_fma_f32 v50, -v69, v70, 1.0
	v_fmac_f32_e32 v70, v50, v70
	v_mul_f32_e32 v50, v71, v70
	v_fma_f32 v51, -v69, v50, v71
	v_fmac_f32_e32 v50, v51, v70
	v_fma_f32 v69, -v69, v50, v71
	v_div_fmas_f32 v69, v69, v70, v50
	v_div_fixup_f32 v207, v69, v68, v207
	v_mul_f32_e32 v32, v207, v32
	s_nop 1
	v_mov_b32_dpp v68, v0 quad_perm:[1,0,3,2] row_mask:0xf bank_mask:0xf
	v_mov_b32_dpp v69, v16 quad_perm:[1,0,3,2] row_mask:0xf bank_mask:0xf
	v_mov_b32_dpp v70, v32 quad_perm:[1,0,3,2] row_mask:0xf bank_mask:0xf
	s_nop 0
	v_cvt_pk_bf16_f32 v0, v0, v68
	v_cvt_pk_bf16_f32 v16, v16, v69
	v_cvt_pk_bf16_f32 v32, v32, v70
	s_mov_b64 exec, s[98:99]
	global_store_dword v202, v0, s[38:39]
	global_store_dword v202, v16, s[38:39] offset:256
	global_store_dword v202, v32, s[38:39] offset:512
	s_mov_b64 exec, -1
	v_add_u32_e32 v202, 0x1000, v202
	s_waitcnt lgkmcnt(0)
	v_add_f32_e32 v68, v64, v65
	v_add_f32_e32 v69, v66, v67
	ds_read_b128 v[64:67], v203 offset:32
	v_add_f32_e32 v68, v68, v69
	v_fmamk_f32 v68, v68, 0x3b2aaaab, v76
	v_mul_f32_e32 v69, 0x4b800000, v68
	v_cmp_gt_f32_e32 vcc, s56, v68
	s_nop 1
	v_cndmask_b32_e32 v68, v68, v69, vcc
	v_rsq_f32_e32 v68, v68
	s_nop 0
	v_mul_f32_e32 v69, 0x45800000, v68
	v_cndmask_b32_e32 v63, v68, v69, vcc
	s_waitcnt vmcnt(47)
	v_lshlrev_b32_e32 v208, 16, v208
	v_add_f32_e32 v208, v195, v208
	v_mul_f32_e32 v68, 0xbfb8aa3b, v208
	v_exp_f32_e32 v68, v68
	v_mul_f32_e32 v1, v1, v63
	v_add_f32_e32 v68, 1.0, v68
	v_div_scale_f32 v69, s[0:1], v68, v68, v208
	v_div_scale_f32 v71, vcc, v208, v68, v208
	v_rcp_f32_e32 v70, v69
	v_mul_f32_e32 v1, v198, v1
	v_fma_f32 v50, -v69, v70, 1.0
	v_fmac_f32_e32 v70, v50, v70
	v_mul_f32_e32 v50, v71, v70
	v_fma_f32 v51, -v69, v50, v71
	v_fmac_f32_e32 v50, v51, v70
	v_fma_f32 v69, -v69, v50, v71
	v_div_fmas_f32 v69, v69, v70, v50
	v_div_fixup_f32 v208, v69, v68, v208
	v_mul_f32_e32 v1, v208, v1
	s_waitcnt vmcnt(46)
	v_lshlrev_b32_e32 v209, 16, v209
	v_add_f32_e32 v209, v196, v209
	v_mul_f32_e32 v68, 0xbfb8aa3b, v209
	v_exp_f32_e32 v68, v68
	v_mul_f32_e32 v17, v17, v63
	v_add_f32_e32 v68, 1.0, v68
	v_div_scale_f32 v69, s[0:1], v68, v68, v209
	v_div_scale_f32 v71, vcc, v209, v68, v209
	v_rcp_f32_e32 v70, v69
	v_mul_f32_e32 v17, v199, v17
	v_fma_f32 v50, -v69, v70, 1.0
	v_fmac_f32_e32 v70, v50, v70
	v_mul_f32_e32 v50, v71, v70
	v_fma_f32 v51, -v69, v50, v71
	v_fmac_f32_e32 v50, v51, v70
	v_fma_f32 v69, -v69, v50, v71
	v_div_fmas_f32 v69, v69, v70, v50
	v_div_fixup_f32 v209, v69, v68, v209
	v_mul_f32_e32 v17, v209, v17
	s_waitcnt vmcnt(45)
	v_lshlrev_b32_e32 v210, 16, v210
	v_add_f32_e32 v210, v197, v210
	v_mul_f32_e32 v68, 0xbfb8aa3b, v210
	v_exp_f32_e32 v68, v68
	v_mul_f32_e32 v33, v33, v63
	v_add_f32_e32 v68, 1.0, v68
	v_div_scale_f32 v69, s[0:1], v68, v68, v210
	v_div_scale_f32 v71, vcc, v210, v68, v210
	v_rcp_f32_e32 v70, v69
	v_mul_f32_e32 v33, v200, v33
	v_fma_f32 v50, -v69, v70, 1.0
	v_fmac_f32_e32 v70, v50, v70
	v_mul_f32_e32 v50, v71, v70
	v_fma_f32 v51, -v69, v50, v71
	v_fmac_f32_e32 v50, v51, v70
	v_fma_f32 v69, -v69, v50, v71
	v_div_fmas_f32 v69, v69, v70, v50
	v_div_fixup_f32 v210, v69, v68, v210
	v_mul_f32_e32 v33, v210, v33
	s_nop 1
	v_mov_b32_dpp v68, v1 quad_perm:[1,0,3,2] row_mask:0xf bank_mask:0xf
	v_mov_b32_dpp v69, v17 quad_perm:[1,0,3,2] row_mask:0xf bank_mask:0xf
	v_mov_b32_dpp v70, v33 quad_perm:[1,0,3,2] row_mask:0xf bank_mask:0xf
	s_nop 0
	v_cvt_pk_bf16_f32 v1, v1, v68
	v_cvt_pk_bf16_f32 v17, v17, v69
	v_cvt_pk_bf16_f32 v33, v33, v70
	s_mov_b64 exec, s[98:99]
	global_store_dword v202, v1, s[38:39]
	global_store_dword v202, v17, s[38:39] offset:256
	global_store_dword v202, v33, s[38:39] offset:512
	s_mov_b64 exec, -1
	v_add_u32_e32 v202, 0x1000, v202
	s_waitcnt lgkmcnt(0)
	v_add_f32_e32 v68, v64, v65
	v_add_f32_e32 v69, v66, v67
	ds_read_b128 v[64:67], v203 offset:48
	v_add_f32_e32 v68, v68, v69
	v_fmamk_f32 v68, v68, 0x3b2aaaab, v76
	v_mul_f32_e32 v69, 0x4b800000, v68
	v_cmp_gt_f32_e32 vcc, s56, v68
	s_nop 1
	v_cndmask_b32_e32 v68, v68, v69, vcc
	v_rsq_f32_e32 v68, v68
	s_nop 0
	v_mul_f32_e32 v69, 0x45800000, v68
	v_cndmask_b32_e32 v63, v68, v69, vcc
	s_waitcnt vmcnt(47)
	v_lshlrev_b32_e32 v211, 16, v211
	v_add_f32_e32 v211, v195, v211
	v_mul_f32_e32 v68, 0xbfb8aa3b, v211
	v_exp_f32_e32 v68, v68
	v_mul_f32_e32 v2, v2, v63
	v_add_f32_e32 v68, 1.0, v68
	v_div_scale_f32 v69, s[0:1], v68, v68, v211
	v_div_scale_f32 v71, vcc, v211, v68, v211
	v_rcp_f32_e32 v70, v69
	v_mul_f32_e32 v2, v198, v2
	v_fma_f32 v50, -v69, v70, 1.0
	v_fmac_f32_e32 v70, v50, v70
	v_mul_f32_e32 v50, v71, v70
	v_fma_f32 v51, -v69, v50, v71
	v_fmac_f32_e32 v50, v51, v70
	v_fma_f32 v69, -v69, v50, v71
	v_div_fmas_f32 v69, v69, v70, v50
	v_div_fixup_f32 v211, v69, v68, v211
	v_mul_f32_e32 v2, v211, v2
	s_waitcnt vmcnt(46)
	v_lshlrev_b32_e32 v212, 16, v212
	v_add_f32_e32 v212, v196, v212
	v_mul_f32_e32 v68, 0xbfb8aa3b, v212
	v_exp_f32_e32 v68, v68
	v_mul_f32_e32 v18, v18, v63
	v_add_f32_e32 v68, 1.0, v68
	v_div_scale_f32 v69, s[0:1], v68, v68, v212
	v_div_scale_f32 v71, vcc, v212, v68, v212
	v_rcp_f32_e32 v70, v69
	v_mul_f32_e32 v18, v199, v18
	v_fma_f32 v50, -v69, v70, 1.0
	v_fmac_f32_e32 v70, v50, v70
	v_mul_f32_e32 v50, v71, v70
	v_fma_f32 v51, -v69, v50, v71
	v_fmac_f32_e32 v50, v51, v70
	v_fma_f32 v69, -v69, v50, v71
	v_div_fmas_f32 v69, v69, v70, v50
	v_div_fixup_f32 v212, v69, v68, v212
	v_mul_f32_e32 v18, v212, v18
	s_waitcnt vmcnt(45)
	v_lshlrev_b32_e32 v213, 16, v213
	v_add_f32_e32 v213, v197, v213
	v_mul_f32_e32 v68, 0xbfb8aa3b, v213
	v_exp_f32_e32 v68, v68
	v_mul_f32_e32 v34, v34, v63
	v_add_f32_e32 v68, 1.0, v68
	v_div_scale_f32 v69, s[0:1], v68, v68, v213
	v_div_scale_f32 v71, vcc, v213, v68, v213
	v_rcp_f32_e32 v70, v69
	v_mul_f32_e32 v34, v200, v34
	v_fma_f32 v50, -v69, v70, 1.0
	v_fmac_f32_e32 v70, v50, v70
	v_mul_f32_e32 v50, v71, v70
	v_fma_f32 v51, -v69, v50, v71
	v_fmac_f32_e32 v50, v51, v70
	v_fma_f32 v69, -v69, v50, v71
	v_div_fmas_f32 v69, v69, v70, v50
	v_div_fixup_f32 v213, v69, v68, v213
	v_mul_f32_e32 v34, v213, v34
	s_nop 1
	v_mov_b32_dpp v68, v2 quad_perm:[1,0,3,2] row_mask:0xf bank_mask:0xf
	v_mov_b32_dpp v69, v18 quad_perm:[1,0,3,2] row_mask:0xf bank_mask:0xf
	v_mov_b32_dpp v70, v34 quad_perm:[1,0,3,2] row_mask:0xf bank_mask:0xf
	s_nop 0
	v_cvt_pk_bf16_f32 v2, v2, v68
	v_cvt_pk_bf16_f32 v18, v18, v69
	v_cvt_pk_bf16_f32 v34, v34, v70
	s_mov_b64 exec, s[98:99]
	global_store_dword v202, v2, s[38:39]
	global_store_dword v202, v18, s[38:39] offset:256
	global_store_dword v202, v34, s[38:39] offset:512
	s_mov_b64 exec, -1
	v_add_u32_e32 v202, 0x1000, v202
	s_waitcnt lgkmcnt(0)
	v_add_f32_e32 v68, v64, v65
	v_add_f32_e32 v69, v66, v67
	ds_read_b128 v[64:67], v203 offset:128
	v_add_f32_e32 v68, v68, v69
	v_fmamk_f32 v68, v68, 0x3b2aaaab, v76
	v_mul_f32_e32 v69, 0x4b800000, v68
	v_cmp_gt_f32_e32 vcc, s56, v68
	s_nop 1
	v_cndmask_b32_e32 v68, v68, v69, vcc
	v_rsq_f32_e32 v68, v68
	s_nop 0
	v_mul_f32_e32 v69, 0x45800000, v68
	v_cndmask_b32_e32 v63, v68, v69, vcc
	s_waitcnt vmcnt(47)
	v_lshlrev_b32_e32 v214, 16, v214
	v_add_f32_e32 v214, v195, v214
	v_mul_f32_e32 v68, 0xbfb8aa3b, v214
	v_exp_f32_e32 v68, v68
	v_mul_f32_e32 v3, v3, v63
	v_add_f32_e32 v68, 1.0, v68
	v_div_scale_f32 v69, s[0:1], v68, v68, v214
	v_div_scale_f32 v71, vcc, v214, v68, v214
	v_rcp_f32_e32 v70, v69
	v_mul_f32_e32 v3, v198, v3
	v_fma_f32 v50, -v69, v70, 1.0
	v_fmac_f32_e32 v70, v50, v70
	v_mul_f32_e32 v50, v71, v70
	v_fma_f32 v51, -v69, v50, v71
	v_fmac_f32_e32 v50, v51, v70
	v_fma_f32 v69, -v69, v50, v71
	v_div_fmas_f32 v69, v69, v70, v50
	v_div_fixup_f32 v214, v69, v68, v214
	v_mul_f32_e32 v3, v214, v3
	s_waitcnt vmcnt(46)
	v_lshlrev_b32_e32 v215, 16, v215
	v_add_f32_e32 v215, v196, v215
	v_mul_f32_e32 v68, 0xbfb8aa3b, v215
	v_exp_f32_e32 v68, v68
	v_mul_f32_e32 v19, v19, v63
	v_add_f32_e32 v68, 1.0, v68
	v_div_scale_f32 v69, s[0:1], v68, v68, v215
	v_div_scale_f32 v71, vcc, v215, v68, v215
	v_rcp_f32_e32 v70, v69
	v_mul_f32_e32 v19, v199, v19
	v_fma_f32 v50, -v69, v70, 1.0
	v_fmac_f32_e32 v70, v50, v70
	v_mul_f32_e32 v50, v71, v70
	v_fma_f32 v51, -v69, v50, v71
	v_fmac_f32_e32 v50, v51, v70
	v_fma_f32 v69, -v69, v50, v71
	v_div_fmas_f32 v69, v69, v70, v50
	v_div_fixup_f32 v215, v69, v68, v215
	v_mul_f32_e32 v19, v215, v19
	s_waitcnt vmcnt(45)
	v_lshlrev_b32_e32 v216, 16, v216
	v_add_f32_e32 v216, v197, v216
	v_mul_f32_e32 v68, 0xbfb8aa3b, v216
	v_exp_f32_e32 v68, v68
	v_mul_f32_e32 v35, v35, v63
	v_add_f32_e32 v68, 1.0, v68
	v_div_scale_f32 v69, s[0:1], v68, v68, v216
	v_div_scale_f32 v71, vcc, v216, v68, v216
	v_rcp_f32_e32 v70, v69
	v_mul_f32_e32 v35, v200, v35
	v_fma_f32 v50, -v69, v70, 1.0
	v_fmac_f32_e32 v70, v50, v70
	v_mul_f32_e32 v50, v71, v70
	v_fma_f32 v51, -v69, v50, v71
	v_fmac_f32_e32 v50, v51, v70
	v_fma_f32 v69, -v69, v50, v71
	v_div_fmas_f32 v69, v69, v70, v50
	v_div_fixup_f32 v216, v69, v68, v216
	v_mul_f32_e32 v35, v216, v35
	s_nop 1
	v_mov_b32_dpp v68, v3 quad_perm:[1,0,3,2] row_mask:0xf bank_mask:0xf
	v_mov_b32_dpp v69, v19 quad_perm:[1,0,3,2] row_mask:0xf bank_mask:0xf
	v_mov_b32_dpp v70, v35 quad_perm:[1,0,3,2] row_mask:0xf bank_mask:0xf
	s_nop 0
	v_cvt_pk_bf16_f32 v3, v3, v68
	v_cvt_pk_bf16_f32 v19, v19, v69
	v_cvt_pk_bf16_f32 v35, v35, v70
	s_mov_b64 exec, s[98:99]
	global_store_dword v202, v3, s[38:39]
	global_store_dword v202, v19, s[38:39] offset:256
	global_store_dword v202, v35, s[38:39] offset:512
	s_mov_b64 exec, -1
	v_add_u32_e32 v202, 0x5000, v202
	s_waitcnt lgkmcnt(0)
	v_add_f32_e32 v68, v64, v65
	v_add_f32_e32 v69, v66, v67
	ds_read_b128 v[64:67], v203 offset:144
	v_add_f32_e32 v68, v68, v69
	v_fmamk_f32 v68, v68, 0x3b2aaaab, v76
	v_mul_f32_e32 v69, 0x4b800000, v68
	v_cmp_gt_f32_e32 vcc, s56, v68
	s_nop 1
	v_cndmask_b32_e32 v68, v68, v69, vcc
	v_rsq_f32_e32 v68, v68
	s_nop 0
	v_mul_f32_e32 v69, 0x45800000, v68
	v_cndmask_b32_e32 v63, v68, v69, vcc
	s_waitcnt vmcnt(47)
	v_lshlrev_b32_e32 v217, 16, v217
	v_add_f32_e32 v217, v195, v217
	v_mul_f32_e32 v68, 0xbfb8aa3b, v217
	v_exp_f32_e32 v68, v68
	v_mul_f32_e32 v4, v4, v63
	v_add_f32_e32 v68, 1.0, v68
	v_div_scale_f32 v69, s[0:1], v68, v68, v217
	v_div_scale_f32 v71, vcc, v217, v68, v217
	v_rcp_f32_e32 v70, v69
	v_mul_f32_e32 v4, v198, v4
	v_fma_f32 v50, -v69, v70, 1.0
	v_fmac_f32_e32 v70, v50, v70
	v_mul_f32_e32 v50, v71, v70
	v_fma_f32 v51, -v69, v50, v71
	v_fmac_f32_e32 v50, v51, v70
	v_fma_f32 v69, -v69, v50, v71
	v_div_fmas_f32 v69, v69, v70, v50
	v_div_fixup_f32 v217, v69, v68, v217
	v_mul_f32_e32 v4, v217, v4
	s_waitcnt vmcnt(46)
	v_lshlrev_b32_e32 v218, 16, v218
	v_add_f32_e32 v218, v196, v218
	v_mul_f32_e32 v68, 0xbfb8aa3b, v218
	v_exp_f32_e32 v68, v68
	v_mul_f32_e32 v20, v20, v63
	v_add_f32_e32 v68, 1.0, v68
	v_div_scale_f32 v69, s[0:1], v68, v68, v218
	v_div_scale_f32 v71, vcc, v218, v68, v218
	v_rcp_f32_e32 v70, v69
	v_mul_f32_e32 v20, v199, v20
	v_fma_f32 v50, -v69, v70, 1.0
	v_fmac_f32_e32 v70, v50, v70
	v_mul_f32_e32 v50, v71, v70
	v_fma_f32 v51, -v69, v50, v71
	v_fmac_f32_e32 v50, v51, v70
	v_fma_f32 v69, -v69, v50, v71
	v_div_fmas_f32 v69, v69, v70, v50
	v_div_fixup_f32 v218, v69, v68, v218
	v_mul_f32_e32 v20, v218, v20
	s_waitcnt vmcnt(45)
	v_lshlrev_b32_e32 v219, 16, v219
	v_add_f32_e32 v219, v197, v219
	v_mul_f32_e32 v68, 0xbfb8aa3b, v219
	v_exp_f32_e32 v68, v68
	v_mul_f32_e32 v36, v36, v63
	v_add_f32_e32 v68, 1.0, v68
	v_div_scale_f32 v69, s[0:1], v68, v68, v219
	v_div_scale_f32 v71, vcc, v219, v68, v219
	v_rcp_f32_e32 v70, v69
	v_mul_f32_e32 v36, v200, v36
	v_fma_f32 v50, -v69, v70, 1.0
	v_fmac_f32_e32 v70, v50, v70
	v_mul_f32_e32 v50, v71, v70
	v_fma_f32 v51, -v69, v50, v71
	v_fmac_f32_e32 v50, v51, v70
	v_fma_f32 v69, -v69, v50, v71
	v_div_fmas_f32 v69, v69, v70, v50
	v_div_fixup_f32 v219, v69, v68, v219
	v_mul_f32_e32 v36, v219, v36
	s_nop 1
	v_mov_b32_dpp v68, v4 quad_perm:[1,0,3,2] row_mask:0xf bank_mask:0xf
	v_mov_b32_dpp v69, v20 quad_perm:[1,0,3,2] row_mask:0xf bank_mask:0xf
	v_mov_b32_dpp v70, v36 quad_perm:[1,0,3,2] row_mask:0xf bank_mask:0xf
	s_nop 0
	v_cvt_pk_bf16_f32 v4, v4, v68
	v_cvt_pk_bf16_f32 v20, v20, v69
	v_cvt_pk_bf16_f32 v36, v36, v70
	s_mov_b64 exec, s[98:99]
	global_store_dword v202, v4, s[38:39]
	global_store_dword v202, v20, s[38:39] offset:256
	global_store_dword v202, v36, s[38:39] offset:512
	s_mov_b64 exec, -1
	v_add_u32_e32 v202, 0x1000, v202
	s_waitcnt lgkmcnt(0)
	v_add_f32_e32 v68, v64, v65
	v_add_f32_e32 v69, v66, v67
	ds_read_b128 v[64:67], v203 offset:160
	v_add_f32_e32 v68, v68, v69
	v_fmamk_f32 v68, v68, 0x3b2aaaab, v76
	v_mul_f32_e32 v69, 0x4b800000, v68
	v_cmp_gt_f32_e32 vcc, s56, v68
	s_nop 1
	v_cndmask_b32_e32 v68, v68, v69, vcc
	v_rsq_f32_e32 v68, v68
	s_nop 0
	v_mul_f32_e32 v69, 0x45800000, v68
	v_cndmask_b32_e32 v63, v68, v69, vcc
	s_waitcnt vmcnt(47)
	v_lshlrev_b32_e32 v220, 16, v220
	v_add_f32_e32 v220, v195, v220
	v_mul_f32_e32 v68, 0xbfb8aa3b, v220
	v_exp_f32_e32 v68, v68
	v_mul_f32_e32 v5, v5, v63
	v_add_f32_e32 v68, 1.0, v68
	v_div_scale_f32 v69, s[0:1], v68, v68, v220
	v_div_scale_f32 v71, vcc, v220, v68, v220
	v_rcp_f32_e32 v70, v69
	v_mul_f32_e32 v5, v198, v5
	v_fma_f32 v50, -v69, v70, 1.0
	v_fmac_f32_e32 v70, v50, v70
	v_mul_f32_e32 v50, v71, v70
	v_fma_f32 v51, -v69, v50, v71
	v_fmac_f32_e32 v50, v51, v70
	v_fma_f32 v69, -v69, v50, v71
	v_div_fmas_f32 v69, v69, v70, v50
	v_div_fixup_f32 v220, v69, v68, v220
	v_mul_f32_e32 v5, v220, v5
	s_waitcnt vmcnt(46)
	v_lshlrev_b32_e32 v221, 16, v221
	v_add_f32_e32 v221, v196, v221
	v_mul_f32_e32 v68, 0xbfb8aa3b, v221
	v_exp_f32_e32 v68, v68
	v_mul_f32_e32 v21, v21, v63
	v_add_f32_e32 v68, 1.0, v68
	v_div_scale_f32 v69, s[0:1], v68, v68, v221
	v_div_scale_f32 v71, vcc, v221, v68, v221
	v_rcp_f32_e32 v70, v69
	v_mul_f32_e32 v21, v199, v21
	v_fma_f32 v50, -v69, v70, 1.0
	v_fmac_f32_e32 v70, v50, v70
	v_mul_f32_e32 v50, v71, v70
	v_fma_f32 v51, -v69, v50, v71
	v_fmac_f32_e32 v50, v51, v70
	v_fma_f32 v69, -v69, v50, v71
	v_div_fmas_f32 v69, v69, v70, v50
	v_div_fixup_f32 v221, v69, v68, v221
	v_mul_f32_e32 v21, v221, v21
	s_waitcnt vmcnt(45)
	v_lshlrev_b32_e32 v222, 16, v222
	v_add_f32_e32 v222, v197, v222
	v_mul_f32_e32 v68, 0xbfb8aa3b, v222
	v_exp_f32_e32 v68, v68
	v_mul_f32_e32 v37, v37, v63
	v_add_f32_e32 v68, 1.0, v68
	v_div_scale_f32 v69, s[0:1], v68, v68, v222
	v_div_scale_f32 v71, vcc, v222, v68, v222
	v_rcp_f32_e32 v70, v69
	v_mul_f32_e32 v37, v200, v37
	v_fma_f32 v50, -v69, v70, 1.0
	v_fmac_f32_e32 v70, v50, v70
	v_mul_f32_e32 v50, v71, v70
	v_fma_f32 v51, -v69, v50, v71
	v_fmac_f32_e32 v50, v51, v70
	v_fma_f32 v69, -v69, v50, v71
	v_div_fmas_f32 v69, v69, v70, v50
	v_div_fixup_f32 v222, v69, v68, v222
	v_mul_f32_e32 v37, v222, v37
	s_nop 1
	v_mov_b32_dpp v68, v5 quad_perm:[1,0,3,2] row_mask:0xf bank_mask:0xf
	v_mov_b32_dpp v69, v21 quad_perm:[1,0,3,2] row_mask:0xf bank_mask:0xf
	v_mov_b32_dpp v70, v37 quad_perm:[1,0,3,2] row_mask:0xf bank_mask:0xf
	s_nop 0
	v_cvt_pk_bf16_f32 v5, v5, v68
	v_cvt_pk_bf16_f32 v21, v21, v69
	v_cvt_pk_bf16_f32 v37, v37, v70
	s_mov_b64 exec, s[98:99]
	global_store_dword v202, v5, s[38:39]
	global_store_dword v202, v21, s[38:39] offset:256
	global_store_dword v202, v37, s[38:39] offset:512
	s_mov_b64 exec, -1
	v_add_u32_e32 v202, 0x1000, v202
	s_waitcnt lgkmcnt(0)
	v_add_f32_e32 v68, v64, v65
	v_add_f32_e32 v69, v66, v67
	ds_read_b128 v[64:67], v203 offset:176
	v_add_f32_e32 v68, v68, v69
	v_fmamk_f32 v68, v68, 0x3b2aaaab, v76
	v_mul_f32_e32 v69, 0x4b800000, v68
	v_cmp_gt_f32_e32 vcc, s56, v68
	s_nop 1
	v_cndmask_b32_e32 v68, v68, v69, vcc
	v_rsq_f32_e32 v68, v68
	s_nop 0
	v_mul_f32_e32 v69, 0x45800000, v68
	v_cndmask_b32_e32 v63, v68, v69, vcc
	s_waitcnt vmcnt(47)
	v_lshlrev_b32_e32 v223, 16, v223
	v_add_f32_e32 v223, v195, v223
	v_mul_f32_e32 v68, 0xbfb8aa3b, v223
	v_exp_f32_e32 v68, v68
	v_mul_f32_e32 v6, v6, v63
	v_add_f32_e32 v68, 1.0, v68
	v_div_scale_f32 v69, s[0:1], v68, v68, v223
	v_div_scale_f32 v71, vcc, v223, v68, v223
	v_rcp_f32_e32 v70, v69
	v_mul_f32_e32 v6, v198, v6
	v_fma_f32 v50, -v69, v70, 1.0
	v_fmac_f32_e32 v70, v50, v70
	v_mul_f32_e32 v50, v71, v70
	v_fma_f32 v51, -v69, v50, v71
	v_fmac_f32_e32 v50, v51, v70
	v_fma_f32 v69, -v69, v50, v71
	v_div_fmas_f32 v69, v69, v70, v50
	v_div_fixup_f32 v223, v69, v68, v223
	v_mul_f32_e32 v6, v223, v6
	s_waitcnt vmcnt(46)
	v_lshlrev_b32_e32 v224, 16, v224
	v_add_f32_e32 v224, v196, v224
	v_mul_f32_e32 v68, 0xbfb8aa3b, v224
	v_exp_f32_e32 v68, v68
	v_mul_f32_e32 v22, v22, v63
	v_add_f32_e32 v68, 1.0, v68
	v_div_scale_f32 v69, s[0:1], v68, v68, v224
	v_div_scale_f32 v71, vcc, v224, v68, v224
	v_rcp_f32_e32 v70, v69
	v_mul_f32_e32 v22, v199, v22
	v_fma_f32 v50, -v69, v70, 1.0
	v_fmac_f32_e32 v70, v50, v70
	v_mul_f32_e32 v50, v71, v70
	v_fma_f32 v51, -v69, v50, v71
	v_fmac_f32_e32 v50, v51, v70
	v_fma_f32 v69, -v69, v50, v71
	v_div_fmas_f32 v69, v69, v70, v50
	v_div_fixup_f32 v224, v69, v68, v224
	v_mul_f32_e32 v22, v224, v22
	s_waitcnt vmcnt(45)
	v_lshlrev_b32_e32 v225, 16, v225
	v_add_f32_e32 v225, v197, v225
	v_mul_f32_e32 v68, 0xbfb8aa3b, v225
	v_exp_f32_e32 v68, v68
	v_mul_f32_e32 v38, v38, v63
	v_add_f32_e32 v68, 1.0, v68
	v_div_scale_f32 v69, s[0:1], v68, v68, v225
	v_div_scale_f32 v71, vcc, v225, v68, v225
	v_rcp_f32_e32 v70, v69
	v_mul_f32_e32 v38, v200, v38
	v_fma_f32 v50, -v69, v70, 1.0
	v_fmac_f32_e32 v70, v50, v70
	v_mul_f32_e32 v50, v71, v70
	v_fma_f32 v51, -v69, v50, v71
	v_fmac_f32_e32 v50, v51, v70
	v_fma_f32 v69, -v69, v50, v71
	v_div_fmas_f32 v69, v69, v70, v50
	v_div_fixup_f32 v225, v69, v68, v225
	v_mul_f32_e32 v38, v225, v38
	s_nop 1
	v_mov_b32_dpp v68, v6 quad_perm:[1,0,3,2] row_mask:0xf bank_mask:0xf
	v_mov_b32_dpp v69, v22 quad_perm:[1,0,3,2] row_mask:0xf bank_mask:0xf
	v_mov_b32_dpp v70, v38 quad_perm:[1,0,3,2] row_mask:0xf bank_mask:0xf
	s_nop 0
	v_cvt_pk_bf16_f32 v6, v6, v68
	v_cvt_pk_bf16_f32 v22, v22, v69
	v_cvt_pk_bf16_f32 v38, v38, v70
	s_mov_b64 exec, s[98:99]
	global_store_dword v202, v6, s[38:39]
	global_store_dword v202, v22, s[38:39] offset:256
	global_store_dword v202, v38, s[38:39] offset:512
	s_mov_b64 exec, -1
	v_add_u32_e32 v202, 0x1000, v202
	s_waitcnt lgkmcnt(0)
	v_add_f32_e32 v68, v64, v65
	v_add_f32_e32 v69, v66, v67
	ds_read_b128 v[64:67], v203 offset:256
	v_add_f32_e32 v68, v68, v69
	v_fmamk_f32 v68, v68, 0x3b2aaaab, v76
	v_mul_f32_e32 v69, 0x4b800000, v68
	v_cmp_gt_f32_e32 vcc, s56, v68
	s_nop 1
	v_cndmask_b32_e32 v68, v68, v69, vcc
	v_rsq_f32_e32 v68, v68
	s_nop 0
	v_mul_f32_e32 v69, 0x45800000, v68
	v_cndmask_b32_e32 v63, v68, v69, vcc
	s_waitcnt vmcnt(47)
	v_lshlrev_b32_e32 v226, 16, v226
	v_add_f32_e32 v226, v195, v226
	v_mul_f32_e32 v68, 0xbfb8aa3b, v226
	v_exp_f32_e32 v68, v68
	v_mul_f32_e32 v7, v7, v63
	v_add_f32_e32 v68, 1.0, v68
	v_div_scale_f32 v69, s[0:1], v68, v68, v226
	v_div_scale_f32 v71, vcc, v226, v68, v226
	v_rcp_f32_e32 v70, v69
	v_mul_f32_e32 v7, v198, v7
	v_fma_f32 v50, -v69, v70, 1.0
	v_fmac_f32_e32 v70, v50, v70
	v_mul_f32_e32 v50, v71, v70
	v_fma_f32 v51, -v69, v50, v71
	v_fmac_f32_e32 v50, v51, v70
	v_fma_f32 v69, -v69, v50, v71
	v_div_fmas_f32 v69, v69, v70, v50
	v_div_fixup_f32 v226, v69, v68, v226
	v_mul_f32_e32 v7, v226, v7
	s_waitcnt vmcnt(46)
	v_lshlrev_b32_e32 v227, 16, v227
	v_add_f32_e32 v227, v196, v227
	v_mul_f32_e32 v68, 0xbfb8aa3b, v227
	v_exp_f32_e32 v68, v68
	v_mul_f32_e32 v23, v23, v63
	v_add_f32_e32 v68, 1.0, v68
	v_div_scale_f32 v69, s[0:1], v68, v68, v227
	v_div_scale_f32 v71, vcc, v227, v68, v227
	v_rcp_f32_e32 v70, v69
	v_mul_f32_e32 v23, v199, v23
	v_fma_f32 v50, -v69, v70, 1.0
	v_fmac_f32_e32 v70, v50, v70
	v_mul_f32_e32 v50, v71, v70
	v_fma_f32 v51, -v69, v50, v71
	v_fmac_f32_e32 v50, v51, v70
	v_fma_f32 v69, -v69, v50, v71
	v_div_fmas_f32 v69, v69, v70, v50
	v_div_fixup_f32 v227, v69, v68, v227
	v_mul_f32_e32 v23, v227, v23
	s_waitcnt vmcnt(45)
	v_lshlrev_b32_e32 v228, 16, v228
	v_add_f32_e32 v228, v197, v228
	v_mul_f32_e32 v68, 0xbfb8aa3b, v228
	v_exp_f32_e32 v68, v68
	v_mul_f32_e32 v39, v39, v63
	v_add_f32_e32 v68, 1.0, v68
	v_div_scale_f32 v69, s[0:1], v68, v68, v228
	v_div_scale_f32 v71, vcc, v228, v68, v228
	v_rcp_f32_e32 v70, v69
	v_mul_f32_e32 v39, v200, v39
	v_fma_f32 v50, -v69, v70, 1.0
	v_fmac_f32_e32 v70, v50, v70
	v_mul_f32_e32 v50, v71, v70
	v_fma_f32 v51, -v69, v50, v71
	v_fmac_f32_e32 v50, v51, v70
	v_fma_f32 v69, -v69, v50, v71
	v_div_fmas_f32 v69, v69, v70, v50
	v_div_fixup_f32 v228, v69, v68, v228
	v_mul_f32_e32 v39, v228, v39
	s_nop 1
	v_mov_b32_dpp v68, v7 quad_perm:[1,0,3,2] row_mask:0xf bank_mask:0xf
	v_mov_b32_dpp v69, v23 quad_perm:[1,0,3,2] row_mask:0xf bank_mask:0xf
	v_mov_b32_dpp v70, v39 quad_perm:[1,0,3,2] row_mask:0xf bank_mask:0xf
	s_nop 0
	v_cvt_pk_bf16_f32 v7, v7, v68
	v_cvt_pk_bf16_f32 v23, v23, v69
	v_cvt_pk_bf16_f32 v39, v39, v70
	s_mov_b64 exec, s[98:99]
	global_store_dword v202, v7, s[38:39]
	global_store_dword v202, v23, s[38:39] offset:256
	global_store_dword v202, v39, s[38:39] offset:512
	s_mov_b64 exec, -1
	v_add_u32_e32 v202, 0x5000, v202
	s_waitcnt lgkmcnt(0)
	v_add_f32_e32 v68, v64, v65
	v_add_f32_e32 v69, v66, v67
	ds_read_b128 v[64:67], v203 offset:272
	v_add_f32_e32 v68, v68, v69
	v_fmamk_f32 v68, v68, 0x3b2aaaab, v76
	v_mul_f32_e32 v69, 0x4b800000, v68
	v_cmp_gt_f32_e32 vcc, s56, v68
	s_nop 1
	v_cndmask_b32_e32 v68, v68, v69, vcc
	v_rsq_f32_e32 v68, v68
	s_nop 0
	v_mul_f32_e32 v69, 0x45800000, v68
	v_cndmask_b32_e32 v63, v68, v69, vcc
	s_waitcnt vmcnt(47)
	v_lshlrev_b32_e32 v229, 16, v229
	v_add_f32_e32 v229, v195, v229
	v_mul_f32_e32 v68, 0xbfb8aa3b, v229
	v_exp_f32_e32 v68, v68
	v_mul_f32_e32 v8, v8, v63
	v_add_f32_e32 v68, 1.0, v68
	v_div_scale_f32 v69, s[0:1], v68, v68, v229
	v_div_scale_f32 v71, vcc, v229, v68, v229
	v_rcp_f32_e32 v70, v69
	v_mul_f32_e32 v8, v198, v8
	v_fma_f32 v50, -v69, v70, 1.0
	v_fmac_f32_e32 v70, v50, v70
	v_mul_f32_e32 v50, v71, v70
	v_fma_f32 v51, -v69, v50, v71
	v_fmac_f32_e32 v50, v51, v70
	v_fma_f32 v69, -v69, v50, v71
	v_div_fmas_f32 v69, v69, v70, v50
	v_div_fixup_f32 v229, v69, v68, v229
	v_mul_f32_e32 v8, v229, v8
	s_waitcnt vmcnt(46)
	v_lshlrev_b32_e32 v230, 16, v230
	v_add_f32_e32 v230, v196, v230
	v_mul_f32_e32 v68, 0xbfb8aa3b, v230
	v_exp_f32_e32 v68, v68
	v_mul_f32_e32 v24, v24, v63
	v_add_f32_e32 v68, 1.0, v68
	v_div_scale_f32 v69, s[0:1], v68, v68, v230
	v_div_scale_f32 v71, vcc, v230, v68, v230
	v_rcp_f32_e32 v70, v69
	v_mul_f32_e32 v24, v199, v24
	v_fma_f32 v50, -v69, v70, 1.0
	v_fmac_f32_e32 v70, v50, v70
	v_mul_f32_e32 v50, v71, v70
	v_fma_f32 v51, -v69, v50, v71
	v_fmac_f32_e32 v50, v51, v70
	v_fma_f32 v69, -v69, v50, v71
	v_div_fmas_f32 v69, v69, v70, v50
	v_div_fixup_f32 v230, v69, v68, v230
	v_mul_f32_e32 v24, v230, v24
	s_waitcnt vmcnt(45)
	v_lshlrev_b32_e32 v231, 16, v231
	v_add_f32_e32 v231, v197, v231
	v_mul_f32_e32 v68, 0xbfb8aa3b, v231
	v_exp_f32_e32 v68, v68
	v_mul_f32_e32 v40, v40, v63
	v_add_f32_e32 v68, 1.0, v68
	v_div_scale_f32 v69, s[0:1], v68, v68, v231
	v_div_scale_f32 v71, vcc, v231, v68, v231
	v_rcp_f32_e32 v70, v69
	v_mul_f32_e32 v40, v200, v40
	v_fma_f32 v50, -v69, v70, 1.0
	v_fmac_f32_e32 v70, v50, v70
	v_mul_f32_e32 v50, v71, v70
	v_fma_f32 v51, -v69, v50, v71
	v_fmac_f32_e32 v50, v51, v70
	v_fma_f32 v69, -v69, v50, v71
	v_div_fmas_f32 v69, v69, v70, v50
	v_div_fixup_f32 v231, v69, v68, v231
	v_mul_f32_e32 v40, v231, v40
	s_nop 1
	v_mov_b32_dpp v68, v8 quad_perm:[1,0,3,2] row_mask:0xf bank_mask:0xf
	v_mov_b32_dpp v69, v24 quad_perm:[1,0,3,2] row_mask:0xf bank_mask:0xf
	v_mov_b32_dpp v70, v40 quad_perm:[1,0,3,2] row_mask:0xf bank_mask:0xf
	s_nop 0
	v_cvt_pk_bf16_f32 v8, v8, v68
	v_cvt_pk_bf16_f32 v24, v24, v69
	v_cvt_pk_bf16_f32 v40, v40, v70
	s_mov_b64 exec, s[98:99]
	global_store_dword v202, v8, s[38:39]
	global_store_dword v202, v24, s[38:39] offset:256
	global_store_dword v202, v40, s[38:39] offset:512
	s_mov_b64 exec, -1
	v_add_u32_e32 v202, 0x1000, v202
	s_waitcnt lgkmcnt(0)
	v_add_f32_e32 v68, v64, v65
	v_add_f32_e32 v69, v66, v67
	ds_read_b128 v[64:67], v203 offset:288
	v_add_f32_e32 v68, v68, v69
	v_fmamk_f32 v68, v68, 0x3b2aaaab, v76
	v_mul_f32_e32 v69, 0x4b800000, v68
	v_cmp_gt_f32_e32 vcc, s56, v68
	s_nop 1
	v_cndmask_b32_e32 v68, v68, v69, vcc
	v_rsq_f32_e32 v68, v68
	s_nop 0
	v_mul_f32_e32 v69, 0x45800000, v68
	v_cndmask_b32_e32 v63, v68, v69, vcc
	s_waitcnt vmcnt(47)
	v_lshlrev_b32_e32 v232, 16, v232
	v_add_f32_e32 v232, v195, v232
	v_mul_f32_e32 v68, 0xbfb8aa3b, v232
	v_exp_f32_e32 v68, v68
	v_mul_f32_e32 v9, v9, v63
	v_add_f32_e32 v68, 1.0, v68
	v_div_scale_f32 v69, s[0:1], v68, v68, v232
	v_div_scale_f32 v71, vcc, v232, v68, v232
	v_rcp_f32_e32 v70, v69
	v_mul_f32_e32 v9, v198, v9
	v_fma_f32 v50, -v69, v70, 1.0
	v_fmac_f32_e32 v70, v50, v70
	v_mul_f32_e32 v50, v71, v70
	v_fma_f32 v51, -v69, v50, v71
	v_fmac_f32_e32 v50, v51, v70
	v_fma_f32 v69, -v69, v50, v71
	v_div_fmas_f32 v69, v69, v70, v50
	v_div_fixup_f32 v232, v69, v68, v232
	v_mul_f32_e32 v9, v232, v9
	s_waitcnt vmcnt(46)
	v_lshlrev_b32_e32 v233, 16, v233
	v_add_f32_e32 v233, v196, v233
	v_mul_f32_e32 v68, 0xbfb8aa3b, v233
	v_exp_f32_e32 v68, v68
	v_mul_f32_e32 v25, v25, v63
	v_add_f32_e32 v68, 1.0, v68
	v_div_scale_f32 v69, s[0:1], v68, v68, v233
	v_div_scale_f32 v71, vcc, v233, v68, v233
	v_rcp_f32_e32 v70, v69
	v_mul_f32_e32 v25, v199, v25
	v_fma_f32 v50, -v69, v70, 1.0
	v_fmac_f32_e32 v70, v50, v70
	v_mul_f32_e32 v50, v71, v70
	v_fma_f32 v51, -v69, v50, v71
	v_fmac_f32_e32 v50, v51, v70
	v_fma_f32 v69, -v69, v50, v71
	v_div_fmas_f32 v69, v69, v70, v50
	v_div_fixup_f32 v233, v69, v68, v233
	v_mul_f32_e32 v25, v233, v25
	s_waitcnt vmcnt(45)
	v_lshlrev_b32_e32 v234, 16, v234
	v_add_f32_e32 v234, v197, v234
	v_mul_f32_e32 v68, 0xbfb8aa3b, v234
	v_exp_f32_e32 v68, v68
	v_mul_f32_e32 v41, v41, v63
	v_add_f32_e32 v68, 1.0, v68
	v_div_scale_f32 v69, s[0:1], v68, v68, v234
	v_div_scale_f32 v71, vcc, v234, v68, v234
	v_rcp_f32_e32 v70, v69
	v_mul_f32_e32 v41, v200, v41
	v_fma_f32 v50, -v69, v70, 1.0
	v_fmac_f32_e32 v70, v50, v70
	v_mul_f32_e32 v50, v71, v70
	v_fma_f32 v51, -v69, v50, v71
	v_fmac_f32_e32 v50, v51, v70
	v_fma_f32 v69, -v69, v50, v71
	v_div_fmas_f32 v69, v69, v70, v50
	v_div_fixup_f32 v234, v69, v68, v234
	v_mul_f32_e32 v41, v234, v41
	s_nop 1
	v_mov_b32_dpp v68, v9 quad_perm:[1,0,3,2] row_mask:0xf bank_mask:0xf
	v_mov_b32_dpp v69, v25 quad_perm:[1,0,3,2] row_mask:0xf bank_mask:0xf
	v_mov_b32_dpp v70, v41 quad_perm:[1,0,3,2] row_mask:0xf bank_mask:0xf
	s_nop 0
	v_cvt_pk_bf16_f32 v9, v9, v68
	v_cvt_pk_bf16_f32 v25, v25, v69
	v_cvt_pk_bf16_f32 v41, v41, v70
	s_mov_b64 exec, s[98:99]
	global_store_dword v202, v9, s[38:39]
	global_store_dword v202, v25, s[38:39] offset:256
	global_store_dword v202, v41, s[38:39] offset:512
	s_mov_b64 exec, -1
	v_add_u32_e32 v202, 0x1000, v202
	s_waitcnt lgkmcnt(0)
	v_add_f32_e32 v68, v64, v65
	v_add_f32_e32 v69, v66, v67
	ds_read_b128 v[64:67], v203 offset:304
	v_add_f32_e32 v68, v68, v69
	v_fmamk_f32 v68, v68, 0x3b2aaaab, v76
	v_mul_f32_e32 v69, 0x4b800000, v68
	v_cmp_gt_f32_e32 vcc, s56, v68
	s_nop 1
	v_cndmask_b32_e32 v68, v68, v69, vcc
	v_rsq_f32_e32 v68, v68
	s_nop 0
	v_mul_f32_e32 v69, 0x45800000, v68
	v_cndmask_b32_e32 v63, v68, v69, vcc
	s_waitcnt vmcnt(47)
	v_lshlrev_b32_e32 v235, 16, v235
	v_add_f32_e32 v235, v195, v235
	v_mul_f32_e32 v68, 0xbfb8aa3b, v235
	v_exp_f32_e32 v68, v68
	v_mul_f32_e32 v10, v10, v63
	v_add_f32_e32 v68, 1.0, v68
	v_div_scale_f32 v69, s[0:1], v68, v68, v235
	v_div_scale_f32 v71, vcc, v235, v68, v235
	v_rcp_f32_e32 v70, v69
	v_mul_f32_e32 v10, v198, v10
	v_fma_f32 v50, -v69, v70, 1.0
	v_fmac_f32_e32 v70, v50, v70
	v_mul_f32_e32 v50, v71, v70
	v_fma_f32 v51, -v69, v50, v71
	v_fmac_f32_e32 v50, v51, v70
	v_fma_f32 v69, -v69, v50, v71
	v_div_fmas_f32 v69, v69, v70, v50
	v_div_fixup_f32 v235, v69, v68, v235
	v_mul_f32_e32 v10, v235, v10
	s_waitcnt vmcnt(46)
	v_lshlrev_b32_e32 v236, 16, v236
	v_add_f32_e32 v236, v196, v236
	v_mul_f32_e32 v68, 0xbfb8aa3b, v236
	v_exp_f32_e32 v68, v68
	v_mul_f32_e32 v26, v26, v63
	v_add_f32_e32 v68, 1.0, v68
	v_div_scale_f32 v69, s[0:1], v68, v68, v236
	v_div_scale_f32 v71, vcc, v236, v68, v236
	v_rcp_f32_e32 v70, v69
	v_mul_f32_e32 v26, v199, v26
	v_fma_f32 v50, -v69, v70, 1.0
	v_fmac_f32_e32 v70, v50, v70
	v_mul_f32_e32 v50, v71, v70
	v_fma_f32 v51, -v69, v50, v71
	v_fmac_f32_e32 v50, v51, v70
	v_fma_f32 v69, -v69, v50, v71
	v_div_fmas_f32 v69, v69, v70, v50
	v_div_fixup_f32 v236, v69, v68, v236
	v_mul_f32_e32 v26, v236, v26
	s_waitcnt vmcnt(45)
	v_lshlrev_b32_e32 v237, 16, v237
	v_add_f32_e32 v237, v197, v237
	v_mul_f32_e32 v68, 0xbfb8aa3b, v237
	v_exp_f32_e32 v68, v68
	v_mul_f32_e32 v42, v42, v63
	v_add_f32_e32 v68, 1.0, v68
	v_div_scale_f32 v69, s[0:1], v68, v68, v237
	v_div_scale_f32 v71, vcc, v237, v68, v237
	v_rcp_f32_e32 v70, v69
	v_mul_f32_e32 v42, v200, v42
	v_fma_f32 v50, -v69, v70, 1.0
	v_fmac_f32_e32 v70, v50, v70
	v_mul_f32_e32 v50, v71, v70
	v_fma_f32 v51, -v69, v50, v71
	v_fmac_f32_e32 v50, v51, v70
	v_fma_f32 v69, -v69, v50, v71
	v_div_fmas_f32 v69, v69, v70, v50
	v_div_fixup_f32 v237, v69, v68, v237
	v_mul_f32_e32 v42, v237, v42
	s_nop 1
	v_mov_b32_dpp v68, v10 quad_perm:[1,0,3,2] row_mask:0xf bank_mask:0xf
	v_mov_b32_dpp v69, v26 quad_perm:[1,0,3,2] row_mask:0xf bank_mask:0xf
	v_mov_b32_dpp v70, v42 quad_perm:[1,0,3,2] row_mask:0xf bank_mask:0xf
	s_nop 0
	v_cvt_pk_bf16_f32 v10, v10, v68
	v_cvt_pk_bf16_f32 v26, v26, v69
	v_cvt_pk_bf16_f32 v42, v42, v70
	s_mov_b64 exec, s[98:99]
	global_store_dword v202, v10, s[38:39]
	global_store_dword v202, v26, s[38:39] offset:256
	global_store_dword v202, v42, s[38:39] offset:512
	s_mov_b64 exec, -1
	v_add_u32_e32 v202, 0x1000, v202
	s_waitcnt lgkmcnt(0)
	v_add_f32_e32 v68, v64, v65
	v_add_f32_e32 v69, v66, v67
	ds_read_b128 v[64:67], v203 offset:384
	v_add_f32_e32 v68, v68, v69
	v_fmamk_f32 v68, v68, 0x3b2aaaab, v76
	v_mul_f32_e32 v69, 0x4b800000, v68
	v_cmp_gt_f32_e32 vcc, s56, v68
	s_nop 1
	v_cndmask_b32_e32 v68, v68, v69, vcc
	v_rsq_f32_e32 v68, v68
	s_nop 0
	v_mul_f32_e32 v69, 0x45800000, v68
	v_cndmask_b32_e32 v63, v68, v69, vcc
	s_waitcnt vmcnt(47)
	v_lshlrev_b32_e32 v238, 16, v238
	v_add_f32_e32 v238, v195, v238
	v_mul_f32_e32 v68, 0xbfb8aa3b, v238
	v_exp_f32_e32 v68, v68
	v_mul_f32_e32 v11, v11, v63
	v_add_f32_e32 v68, 1.0, v68
	v_div_scale_f32 v69, s[0:1], v68, v68, v238
	v_div_scale_f32 v71, vcc, v238, v68, v238
	v_rcp_f32_e32 v70, v69
	v_mul_f32_e32 v11, v198, v11
	v_fma_f32 v50, -v69, v70, 1.0
	v_fmac_f32_e32 v70, v50, v70
	v_mul_f32_e32 v50, v71, v70
	v_fma_f32 v51, -v69, v50, v71
	v_fmac_f32_e32 v50, v51, v70
	v_fma_f32 v69, -v69, v50, v71
	v_div_fmas_f32 v69, v69, v70, v50
	v_div_fixup_f32 v238, v69, v68, v238
	v_mul_f32_e32 v11, v238, v11
	s_waitcnt vmcnt(46)
	v_lshlrev_b32_e32 v239, 16, v239
	v_add_f32_e32 v239, v196, v239
	v_mul_f32_e32 v68, 0xbfb8aa3b, v239
	v_exp_f32_e32 v68, v68
	v_mul_f32_e32 v27, v27, v63
	v_add_f32_e32 v68, 1.0, v68
	v_div_scale_f32 v69, s[0:1], v68, v68, v239
	v_div_scale_f32 v71, vcc, v239, v68, v239
	v_rcp_f32_e32 v70, v69
	v_mul_f32_e32 v27, v199, v27
	v_fma_f32 v50, -v69, v70, 1.0
	v_fmac_f32_e32 v70, v50, v70
	v_mul_f32_e32 v50, v71, v70
	v_fma_f32 v51, -v69, v50, v71
	v_fmac_f32_e32 v50, v51, v70
	v_fma_f32 v69, -v69, v50, v71
	v_div_fmas_f32 v69, v69, v70, v50
	v_div_fixup_f32 v239, v69, v68, v239
	v_mul_f32_e32 v27, v239, v27
	s_waitcnt vmcnt(45)
	v_lshlrev_b32_e32 v240, 16, v240
	v_add_f32_e32 v240, v197, v240
	v_mul_f32_e32 v68, 0xbfb8aa3b, v240
	v_exp_f32_e32 v68, v68
	v_mul_f32_e32 v43, v43, v63
	v_add_f32_e32 v68, 1.0, v68
	v_div_scale_f32 v69, s[0:1], v68, v68, v240
	v_div_scale_f32 v71, vcc, v240, v68, v240
	v_rcp_f32_e32 v70, v69
	v_mul_f32_e32 v43, v200, v43
	v_fma_f32 v50, -v69, v70, 1.0
	v_fmac_f32_e32 v70, v50, v70
	v_mul_f32_e32 v50, v71, v70
	v_fma_f32 v51, -v69, v50, v71
	v_fmac_f32_e32 v50, v51, v70
	v_fma_f32 v69, -v69, v50, v71
	v_div_fmas_f32 v69, v69, v70, v50
	v_div_fixup_f32 v240, v69, v68, v240
	v_mul_f32_e32 v43, v240, v43
	s_nop 1
	v_mov_b32_dpp v68, v11 quad_perm:[1,0,3,2] row_mask:0xf bank_mask:0xf
	v_mov_b32_dpp v69, v27 quad_perm:[1,0,3,2] row_mask:0xf bank_mask:0xf
	v_mov_b32_dpp v70, v43 quad_perm:[1,0,3,2] row_mask:0xf bank_mask:0xf
	s_nop 0
	v_cvt_pk_bf16_f32 v11, v11, v68
	v_cvt_pk_bf16_f32 v27, v27, v69
	v_cvt_pk_bf16_f32 v43, v43, v70
	s_mov_b64 exec, s[98:99]
	global_store_dword v202, v11, s[38:39]
	global_store_dword v202, v27, s[38:39] offset:256
	global_store_dword v202, v43, s[38:39] offset:512
	s_mov_b64 exec, -1
	v_add_u32_e32 v202, 0x5000, v202
	s_waitcnt lgkmcnt(0)
	v_add_f32_e32 v68, v64, v65
	v_add_f32_e32 v69, v66, v67
	ds_read_b128 v[64:67], v203 offset:400
	v_add_f32_e32 v68, v68, v69
	v_fmamk_f32 v68, v68, 0x3b2aaaab, v76
	v_mul_f32_e32 v69, 0x4b800000, v68
	v_cmp_gt_f32_e32 vcc, s56, v68
	s_nop 1
	v_cndmask_b32_e32 v68, v68, v69, vcc
	v_rsq_f32_e32 v68, v68
	s_nop 0
	v_mul_f32_e32 v69, 0x45800000, v68
	v_cndmask_b32_e32 v63, v68, v69, vcc
	s_waitcnt vmcnt(47)
	v_lshlrev_b32_e32 v241, 16, v241
	v_add_f32_e32 v241, v195, v241
	v_mul_f32_e32 v68, 0xbfb8aa3b, v241
	v_exp_f32_e32 v68, v68
	v_mul_f32_e32 v12, v12, v63
	v_add_f32_e32 v68, 1.0, v68
	v_div_scale_f32 v69, s[0:1], v68, v68, v241
	v_div_scale_f32 v71, vcc, v241, v68, v241
	v_rcp_f32_e32 v70, v69
	v_mul_f32_e32 v12, v198, v12
	v_fma_f32 v50, -v69, v70, 1.0
	v_fmac_f32_e32 v70, v50, v70
	v_mul_f32_e32 v50, v71, v70
	v_fma_f32 v51, -v69, v50, v71
	v_fmac_f32_e32 v50, v51, v70
	v_fma_f32 v69, -v69, v50, v71
	v_div_fmas_f32 v69, v69, v70, v50
	v_div_fixup_f32 v241, v69, v68, v241
	v_mul_f32_e32 v12, v241, v12
	s_waitcnt vmcnt(46)
	v_lshlrev_b32_e32 v242, 16, v242
	v_add_f32_e32 v242, v196, v242
	v_mul_f32_e32 v68, 0xbfb8aa3b, v242
	v_exp_f32_e32 v68, v68
	v_mul_f32_e32 v28, v28, v63
	v_add_f32_e32 v68, 1.0, v68
	v_div_scale_f32 v69, s[0:1], v68, v68, v242
	v_div_scale_f32 v71, vcc, v242, v68, v242
	v_rcp_f32_e32 v70, v69
	v_mul_f32_e32 v28, v199, v28
	v_fma_f32 v50, -v69, v70, 1.0
	v_fmac_f32_e32 v70, v50, v70
	v_mul_f32_e32 v50, v71, v70
	v_fma_f32 v51, -v69, v50, v71
	v_fmac_f32_e32 v50, v51, v70
	v_fma_f32 v69, -v69, v50, v71
	v_div_fmas_f32 v69, v69, v70, v50
	v_div_fixup_f32 v242, v69, v68, v242
	v_mul_f32_e32 v28, v242, v28
	s_waitcnt vmcnt(45)
	v_lshlrev_b32_e32 v243, 16, v243
	v_add_f32_e32 v243, v197, v243
	v_mul_f32_e32 v68, 0xbfb8aa3b, v243
	v_exp_f32_e32 v68, v68
	v_mul_f32_e32 v44, v44, v63
	v_add_f32_e32 v68, 1.0, v68
	v_div_scale_f32 v69, s[0:1], v68, v68, v243
	v_div_scale_f32 v71, vcc, v243, v68, v243
	v_rcp_f32_e32 v70, v69
	v_mul_f32_e32 v44, v200, v44
	v_fma_f32 v50, -v69, v70, 1.0
	v_fmac_f32_e32 v70, v50, v70
	v_mul_f32_e32 v50, v71, v70
	v_fma_f32 v51, -v69, v50, v71
	v_fmac_f32_e32 v50, v51, v70
	v_fma_f32 v69, -v69, v50, v71
	v_div_fmas_f32 v69, v69, v70, v50
	v_div_fixup_f32 v243, v69, v68, v243
	v_mul_f32_e32 v44, v243, v44
	s_nop 1
	v_mov_b32_dpp v68, v12 quad_perm:[1,0,3,2] row_mask:0xf bank_mask:0xf
	v_mov_b32_dpp v69, v28 quad_perm:[1,0,3,2] row_mask:0xf bank_mask:0xf
	v_mov_b32_dpp v70, v44 quad_perm:[1,0,3,2] row_mask:0xf bank_mask:0xf
	s_nop 0
	v_cvt_pk_bf16_f32 v12, v12, v68
	v_cvt_pk_bf16_f32 v28, v28, v69
	v_cvt_pk_bf16_f32 v44, v44, v70
	s_mov_b64 exec, s[98:99]
	global_store_dword v202, v12, s[38:39]
	global_store_dword v202, v28, s[38:39] offset:256
	global_store_dword v202, v44, s[38:39] offset:512
	s_mov_b64 exec, -1
	v_add_u32_e32 v202, 0x1000, v202
	s_waitcnt lgkmcnt(0)
	v_add_f32_e32 v68, v64, v65
	v_add_f32_e32 v69, v66, v67
	ds_read_b128 v[64:67], v203 offset:416
	v_add_f32_e32 v68, v68, v69
	v_fmamk_f32 v68, v68, 0x3b2aaaab, v76
	v_mul_f32_e32 v69, 0x4b800000, v68
	v_cmp_gt_f32_e32 vcc, s56, v68
	s_nop 1
	v_cndmask_b32_e32 v68, v68, v69, vcc
	v_rsq_f32_e32 v68, v68
	s_nop 0
	v_mul_f32_e32 v69, 0x45800000, v68
	v_cndmask_b32_e32 v63, v68, v69, vcc
	s_waitcnt vmcnt(47)
	v_lshlrev_b32_e32 v244, 16, v244
	v_add_f32_e32 v244, v195, v244
	v_mul_f32_e32 v68, 0xbfb8aa3b, v244
	v_exp_f32_e32 v68, v68
	v_mul_f32_e32 v13, v13, v63
	v_add_f32_e32 v68, 1.0, v68
	v_div_scale_f32 v69, s[0:1], v68, v68, v244
	v_div_scale_f32 v71, vcc, v244, v68, v244
	v_rcp_f32_e32 v70, v69
	v_mul_f32_e32 v13, v198, v13
	v_fma_f32 v50, -v69, v70, 1.0
	v_fmac_f32_e32 v70, v50, v70
	v_mul_f32_e32 v50, v71, v70
	v_fma_f32 v51, -v69, v50, v71
	v_fmac_f32_e32 v50, v51, v70
	v_fma_f32 v69, -v69, v50, v71
	v_div_fmas_f32 v69, v69, v70, v50
	v_div_fixup_f32 v244, v69, v68, v244
	v_mul_f32_e32 v13, v244, v13
	s_waitcnt vmcnt(46)
	v_lshlrev_b32_e32 v245, 16, v245
	v_add_f32_e32 v245, v196, v245
	v_mul_f32_e32 v68, 0xbfb8aa3b, v245
	v_exp_f32_e32 v68, v68
	v_mul_f32_e32 v29, v29, v63
	v_add_f32_e32 v68, 1.0, v68
	v_div_scale_f32 v69, s[0:1], v68, v68, v245
	v_div_scale_f32 v71, vcc, v245, v68, v245
	v_rcp_f32_e32 v70, v69
	v_mul_f32_e32 v29, v199, v29
	v_fma_f32 v50, -v69, v70, 1.0
	v_fmac_f32_e32 v70, v50, v70
	v_mul_f32_e32 v50, v71, v70
	v_fma_f32 v51, -v69, v50, v71
	v_fmac_f32_e32 v50, v51, v70
	v_fma_f32 v69, -v69, v50, v71
	v_div_fmas_f32 v69, v69, v70, v50
	v_div_fixup_f32 v245, v69, v68, v245
	v_mul_f32_e32 v29, v245, v29
	s_waitcnt vmcnt(45)
	v_lshlrev_b32_e32 v246, 16, v246
	v_add_f32_e32 v246, v197, v246
	v_mul_f32_e32 v68, 0xbfb8aa3b, v246
	v_exp_f32_e32 v68, v68
	v_mul_f32_e32 v45, v45, v63
	v_add_f32_e32 v68, 1.0, v68
	v_div_scale_f32 v69, s[0:1], v68, v68, v246
	v_div_scale_f32 v71, vcc, v246, v68, v246
	v_rcp_f32_e32 v70, v69
	v_mul_f32_e32 v45, v200, v45
	v_fma_f32 v50, -v69, v70, 1.0
	v_fmac_f32_e32 v70, v50, v70
	v_mul_f32_e32 v50, v71, v70
	v_fma_f32 v51, -v69, v50, v71
	v_fmac_f32_e32 v50, v51, v70
	v_fma_f32 v69, -v69, v50, v71
	v_div_fmas_f32 v69, v69, v70, v50
	v_div_fixup_f32 v246, v69, v68, v246
	v_mul_f32_e32 v45, v246, v45
	s_nop 1
	v_mov_b32_dpp v68, v13 quad_perm:[1,0,3,2] row_mask:0xf bank_mask:0xf
	v_mov_b32_dpp v69, v29 quad_perm:[1,0,3,2] row_mask:0xf bank_mask:0xf
	v_mov_b32_dpp v70, v45 quad_perm:[1,0,3,2] row_mask:0xf bank_mask:0xf
	s_nop 0
	v_cvt_pk_bf16_f32 v13, v13, v68
	v_cvt_pk_bf16_f32 v29, v29, v69
	v_cvt_pk_bf16_f32 v45, v45, v70
	s_mov_b64 exec, s[98:99]
	global_store_dword v202, v13, s[38:39]
	global_store_dword v202, v29, s[38:39] offset:256
	global_store_dword v202, v45, s[38:39] offset:512
	s_mov_b64 exec, -1
	v_add_u32_e32 v202, 0x1000, v202
	s_waitcnt lgkmcnt(0)
	v_add_f32_e32 v68, v64, v65
	v_add_f32_e32 v69, v66, v67
	ds_read_b128 v[64:67], v203 offset:432
	v_add_f32_e32 v68, v68, v69
	v_fmamk_f32 v68, v68, 0x3b2aaaab, v76
	v_mul_f32_e32 v69, 0x4b800000, v68
	v_cmp_gt_f32_e32 vcc, s56, v68
	s_nop 1
	v_cndmask_b32_e32 v68, v68, v69, vcc
	v_rsq_f32_e32 v68, v68
	s_nop 0
	v_mul_f32_e32 v69, 0x45800000, v68
	v_cndmask_b32_e32 v63, v68, v69, vcc
	s_waitcnt vmcnt(47)
	v_lshlrev_b32_e32 v247, 16, v247
	v_add_f32_e32 v247, v195, v247
	v_mul_f32_e32 v68, 0xbfb8aa3b, v247
	v_exp_f32_e32 v68, v68
	v_mul_f32_e32 v14, v14, v63
	v_add_f32_e32 v68, 1.0, v68
	v_div_scale_f32 v69, s[0:1], v68, v68, v247
	v_div_scale_f32 v71, vcc, v247, v68, v247
	v_rcp_f32_e32 v70, v69
	v_mul_f32_e32 v14, v198, v14
	v_fma_f32 v50, -v69, v70, 1.0
	v_fmac_f32_e32 v70, v50, v70
	v_mul_f32_e32 v50, v71, v70
	v_fma_f32 v51, -v69, v50, v71
	v_fmac_f32_e32 v50, v51, v70
	v_fma_f32 v69, -v69, v50, v71
	v_div_fmas_f32 v69, v69, v70, v50
	v_div_fixup_f32 v247, v69, v68, v247
	v_mul_f32_e32 v14, v247, v14
	s_waitcnt vmcnt(46)
	v_lshlrev_b32_e32 v248, 16, v248
	v_add_f32_e32 v248, v196, v248
	v_mul_f32_e32 v68, 0xbfb8aa3b, v248
	v_exp_f32_e32 v68, v68
	v_mul_f32_e32 v30, v30, v63
	v_add_f32_e32 v68, 1.0, v68
	v_div_scale_f32 v69, s[0:1], v68, v68, v248
	v_div_scale_f32 v71, vcc, v248, v68, v248
	v_rcp_f32_e32 v70, v69
	v_mul_f32_e32 v30, v199, v30
	v_fma_f32 v50, -v69, v70, 1.0
	v_fmac_f32_e32 v70, v50, v70
	v_mul_f32_e32 v50, v71, v70
	v_fma_f32 v51, -v69, v50, v71
	v_fmac_f32_e32 v50, v51, v70
	v_fma_f32 v69, -v69, v50, v71
	v_div_fmas_f32 v69, v69, v70, v50
	v_div_fixup_f32 v248, v69, v68, v248
	v_mul_f32_e32 v30, v248, v30
	s_waitcnt vmcnt(45)
	v_lshlrev_b32_e32 v249, 16, v249
	v_add_f32_e32 v249, v197, v249
	v_mul_f32_e32 v68, 0xbfb8aa3b, v249
	v_exp_f32_e32 v68, v68
	v_mul_f32_e32 v46, v46, v63
	v_add_f32_e32 v68, 1.0, v68
	v_div_scale_f32 v69, s[0:1], v68, v68, v249
	v_div_scale_f32 v71, vcc, v249, v68, v249
	v_rcp_f32_e32 v70, v69
	v_mul_f32_e32 v46, v200, v46
	v_fma_f32 v50, -v69, v70, 1.0
	v_fmac_f32_e32 v70, v50, v70
	v_mul_f32_e32 v50, v71, v70
	v_fma_f32 v51, -v69, v50, v71
	v_fmac_f32_e32 v50, v51, v70
	v_fma_f32 v69, -v69, v50, v71
	v_div_fmas_f32 v69, v69, v70, v50
	v_div_fixup_f32 v249, v69, v68, v249
	v_mul_f32_e32 v46, v249, v46
	s_nop 1
	v_mov_b32_dpp v68, v14 quad_perm:[1,0,3,2] row_mask:0xf bank_mask:0xf
	v_mov_b32_dpp v69, v30 quad_perm:[1,0,3,2] row_mask:0xf bank_mask:0xf
	v_mov_b32_dpp v70, v46 quad_perm:[1,0,3,2] row_mask:0xf bank_mask:0xf
	s_nop 0
	v_cvt_pk_bf16_f32 v14, v14, v68
	v_cvt_pk_bf16_f32 v30, v30, v69
	v_cvt_pk_bf16_f32 v46, v46, v70
	s_mov_b64 exec, s[98:99]
	global_store_dword v202, v14, s[38:39]
	global_store_dword v202, v30, s[38:39] offset:256
	global_store_dword v202, v46, s[38:39] offset:512
	s_mov_b64 exec, -1
	v_add_u32_e32 v202, 0x1000, v202
	s_waitcnt lgkmcnt(0)
	v_add_f32_e32 v68, v64, v65
	v_add_f32_e32 v69, v66, v67
	v_add_f32_e32 v68, v68, v69
	v_fmamk_f32 v68, v68, 0x3b2aaaab, v76
	v_mul_f32_e32 v69, 0x4b800000, v68
	v_cmp_gt_f32_e32 vcc, s56, v68
	s_nop 1
	v_cndmask_b32_e32 v68, v68, v69, vcc
	v_rsq_f32_e32 v68, v68
	s_nop 0
	v_mul_f32_e32 v69, 0x45800000, v68
	v_cndmask_b32_e32 v63, v68, v69, vcc
	s_waitcnt vmcnt(47)
	v_lshlrev_b32_e32 v250, 16, v250
	v_add_f32_e32 v250, v195, v250
	v_mul_f32_e32 v68, 0xbfb8aa3b, v250
	v_exp_f32_e32 v68, v68
	v_mul_f32_e32 v15, v15, v63
	v_add_f32_e32 v68, 1.0, v68
	v_div_scale_f32 v69, s[0:1], v68, v68, v250
	v_div_scale_f32 v71, vcc, v250, v68, v250
	v_rcp_f32_e32 v70, v69
	v_mul_f32_e32 v15, v198, v15
	v_fma_f32 v50, -v69, v70, 1.0
	v_fmac_f32_e32 v70, v50, v70
	v_mul_f32_e32 v50, v71, v70
	v_fma_f32 v51, -v69, v50, v71
	v_fmac_f32_e32 v50, v51, v70
	v_fma_f32 v69, -v69, v50, v71
	v_div_fmas_f32 v69, v69, v70, v50
	v_div_fixup_f32 v250, v69, v68, v250
	v_mul_f32_e32 v15, v250, v15
	s_waitcnt vmcnt(46)
	v_lshlrev_b32_e32 v251, 16, v251
	v_add_f32_e32 v251, v196, v251
	v_mul_f32_e32 v68, 0xbfb8aa3b, v251
	v_exp_f32_e32 v68, v68
	v_mul_f32_e32 v31, v31, v63
	v_add_f32_e32 v68, 1.0, v68
	v_div_scale_f32 v69, s[0:1], v68, v68, v251
	v_div_scale_f32 v71, vcc, v251, v68, v251
	v_rcp_f32_e32 v70, v69
	v_mul_f32_e32 v31, v199, v31
	v_fma_f32 v50, -v69, v70, 1.0
	v_fmac_f32_e32 v70, v50, v70
	v_mul_f32_e32 v50, v71, v70
	v_fma_f32 v51, -v69, v50, v71
	v_fmac_f32_e32 v50, v51, v70
	v_fma_f32 v69, -v69, v50, v71
	v_div_fmas_f32 v69, v69, v70, v50
	v_div_fixup_f32 v251, v69, v68, v251
	v_mul_f32_e32 v31, v251, v31
	s_waitcnt vmcnt(45)
	v_lshlrev_b32_e32 v194, 16, v194
	v_add_f32_e32 v194, v197, v194
	v_mul_f32_e32 v68, 0xbfb8aa3b, v194
	v_exp_f32_e32 v68, v68
	v_mul_f32_e32 v47, v47, v63
	v_add_f32_e32 v68, 1.0, v68
	v_div_scale_f32 v69, s[0:1], v68, v68, v194
	v_div_scale_f32 v71, vcc, v194, v68, v194
	v_rcp_f32_e32 v70, v69
	v_mul_f32_e32 v47, v200, v47
	v_fma_f32 v50, -v69, v70, 1.0
	v_fmac_f32_e32 v70, v50, v70
	v_mul_f32_e32 v50, v71, v70
	v_fma_f32 v51, -v69, v50, v71
	v_fmac_f32_e32 v50, v51, v70
	v_fma_f32 v69, -v69, v50, v71
	v_div_fmas_f32 v69, v69, v70, v50
	v_div_fixup_f32 v194, v69, v68, v194
	v_mul_f32_e32 v47, v194, v47
	s_nop 1
	v_mov_b32_dpp v68, v15 quad_perm:[1,0,3,2] row_mask:0xf bank_mask:0xf
	v_mov_b32_dpp v69, v31 quad_perm:[1,0,3,2] row_mask:0xf bank_mask:0xf
	v_mov_b32_dpp v70, v47 quad_perm:[1,0,3,2] row_mask:0xf bank_mask:0xf
	s_nop 0
	v_cvt_pk_bf16_f32 v15, v15, v68
	v_cvt_pk_bf16_f32 v31, v31, v69
	v_cvt_pk_bf16_f32 v47, v47, v70
	s_mov_b64 exec, s[98:99]
	global_store_dword v202, v15, s[38:39]
	global_store_dword v202, v31, s[38:39] offset:256
	global_store_dword v202, v47, s[38:39] offset:512
	s_mov_b64 exec, -1
	s_branch .LBB0_4791
